# grid barrier: acquire-side cache invalidate issued at arrival (hidden behind the wait) instead of after the release is observed
# speedup vs baseline: 1.0161x; 1.0066x over previous
; __device__ __forceinline__ unsigned xb_ld(unsigned* p)              { return __hip_atomic_load(p, __ATOMIC_RELAXED, __HIP_MEMORY_SCOPE_AGENT); }
; __device__ __forceinline__ unsigned xb_add(unsigned* p, unsigned v) { return __hip_atomic_fetch_add(p, v, __ATOMIC_RELAXED, __HIP_MEMORY_SCOPE_AGENT); }
; #define XB_SPIN(cond, bar) do { unsigned _sp = 0; while (cond) { __builtin_amdgcn_s_sleep(1); \
;     if ((++_sp & 255u) == 0u) { if (xb_ld(&(bar)[XB_TMO])) break; if (_sp > XB_SPIN_CAP) { atomicAdd(&(bar)[XB_TMO], 1u); break; } } } } while (0)
; __device__ __forceinline__ void xcd_barrier(const XcdBarrier& b) {
;     ...
;         const unsigned old = xb_add(&bar[XB_XSUB(b.x)], 1u);
;         const unsigned gen = old / nloc;
;         if (old + 1u == (gen + 1u) * nloc) {
;             __builtin_amdgcn_fence(__ATOMIC_RELEASE, "agent");
;             asm volatile("s_waitcnt vmcnt(0)" ::: "memory");
;             const unsigned og = xb_add(&bar[XB_TOP], 1u);
;             const unsigned tg = og / nx;
;             if (og + 1u == (tg + 1u) * nx) xb_add(&bar[XB_TOPGEN], 1u);
;             else XB_SPIN(xb_ld(&bar[XB_TOPGEN]) == tg, bar);
;             __builtin_amdgcn_fence(__ATOMIC_ACQUIRE, "agent");
;             xb_add(&bar[XB_XGEN(b.x)], 1u);
;             asm volatile("s_waitcnt vmcnt(0)" ::: "memory");
;         } else {
;             XB_SPIN(xb_ld(&bar[XB_XGEN(b.x)]) == gen, bar);
.LBB0_377:
	s_or_b64 exec, exec, s[6:7]
	v_cvt_f32_u32_e32 v5, v3
	s_waitcnt vmcnt(0)
	v_readfirstlane_b32 s4, v4
	buffer_inv sc1
	v_sub_u32_e32 v4, 0, v3
	v_rcp_iflag_f32_e32 v5, v5
	v_add_u32_e32 v6, s4, v2
	v_mul_f32_e32 v5, 0x4f7ffffe, v5
	v_cvt_u32_f32_e32 v5, v5
	v_mul_lo_u32 v2, v4, v5
	v_mul_hi_u32 v2, v5, v2
	v_add_u32_e32 v2, v5, v2
	v_mul_hi_u32 v2, v6, v2
	v_mul_lo_u32 v4, v2, v3
	v_sub_u32_e32 v4, v6, v4
	v_add_u32_e32 v5, 1, v2
	v_sub_u32_e32 v7, v4, v3
	v_cmp_ge_u32_e32 vcc, v4, v3
	s_nop 1
	v_cndmask_b32_e32 v2, v2, v5, vcc
	v_cndmask_b32_e32 v4, v4, v7, vcc
	v_add_u32_e32 v5, 1, v2
	v_cmp_ge_u32_e32 vcc, v4, v3
	v_add_u32_e32 v4, 1, v6
	s_nop 0
	v_cndmask_b32_e32 v2, v2, v5, vcc
	v_mul_lo_u32 v5, v3, v2
	v_add_u32_e32 v3, v5, v3
	v_cmp_ne_u32_e32 vcc, v4, v3
	s_and_saveexec_b64 s[6:7], vcc
	s_xor_b64 s[6:7], exec, s[6:7]
	s_cbranch_execz .LBB0_391
	v_readlane_b32 s8, v253, 36
	v_readlane_b32 s9, v253, 37
	s_waitcnt lgkmcnt(0)
	s_nop 3
	global_load_dword v1, v99, s[8:9] sc1
	s_waitcnt vmcnt(0)
	v_cmp_eq_u32_e32 vcc, v1, v2
	s_and_saveexec_b64 s[8:9], vcc
	s_cbranch_execz .LBB0_390
	s_mov_b32 s4, 1
	s_mov_b64 s[10:11], 0
	s_branch .LBB0_381

; __device__ __forceinline__ unsigned xb_ld(unsigned* p)              { return __hip_atomic_load(p, __ATOMIC_RELAXED, __HIP_MEMORY_SCOPE_AGENT); }
; #define XB_SPIN(cond, bar) do { unsigned _sp = 0; while (cond) { __builtin_amdgcn_s_sleep(1); \
;     if ((++_sp & 255u) == 0u) { if (xb_ld(&(bar)[XB_TMO])) break; if (_sp > XB_SPIN_CAP) { atomicAdd(&(bar)[XB_TMO], 1u); break; } } } } while (0)
; __device__ __forceinline__ void xcd_barrier(const XcdBarrier& b) {
;     ...
;         } else {
;             XB_SPIN(xb_ld(&bar[XB_XGEN(b.x)]) == gen, bar);
;             __builtin_amdgcn_fence(__ATOMIC_ACQUIRE, "agent");
;             asm volatile("s_waitcnt vmcnt(0)" ::: "memory");
.LBB0_390:
	s_or_b64 exec, exec, s[8:9]
	s_waitcnt vmcnt(0)
	s_waitcnt vmcnt(0)

; __device__ __forceinline__ unsigned xb_add(unsigned* p, unsigned v) { return __hip_atomic_fetch_add(p, v, __ATOMIC_RELAXED, __HIP_MEMORY_SCOPE_AGENT); }
; __device__ __forceinline__ void xcd_barrier(const XcdBarrier& b) {
;     ...
;             __builtin_amdgcn_fence(__ATOMIC_ACQUIRE, "agent");
;             xb_add(&bar[XB_XGEN(b.x)], 1u);
;             asm volatile("s_waitcnt vmcnt(0)" ::: "memory");
.LBB0_408:
	s_or_b64 exec, exec, s[6:7]
	s_mov_b64 s[6:7], exec
	v_mbcnt_lo_u32_b32 v1, s6, 0
	v_mbcnt_hi_u32_b32 v1, s7, v1
	v_cmp_eq_u32_e32 vcc, 0, v1
	s_waitcnt vmcnt(0)
	s_and_saveexec_b64 s[8:9], vcc
	s_cbranch_execz .LBB0_410
	s_bcnt1_i32_b64 s4, s[6:7]
	v_readlane_b32 s6, v253, 36
	v_mov_b32_e32 v1, s4
	v_readlane_b32 s7, v253, 37
	s_nop 4
	global_atomic_add v99, v1, s[6:7]

; __device__ __forceinline__ unsigned xb_ld(unsigned* p)              { return __hip_atomic_load(p, __ATOMIC_RELAXED, __HIP_MEMORY_SCOPE_AGENT); }
; __device__ __forceinline__ unsigned xb_add(unsigned* p, unsigned v) { return __hip_atomic_fetch_add(p, v, __ATOMIC_RELAXED, __HIP_MEMORY_SCOPE_AGENT); }
; #define XB_SPIN(cond, bar) do { unsigned _sp = 0; while (cond) { __builtin_amdgcn_s_sleep(1); \
;     if ((++_sp & 255u) == 0u) { if (xb_ld(&(bar)[XB_TMO])) break; if (_sp > XB_SPIN_CAP) { atomicAdd(&(bar)[XB_TMO], 1u); break; } } } } while (0)
; __device__ __forceinline__ void xcd_barrier(const XcdBarrier& b) {
;     ...
;         const unsigned old = xb_add(&bar[XB_XSUB(b.x)], 1u);
;         const unsigned gen = old / nloc;
;         if (old + 1u == (gen + 1u) * nloc) {
;             __builtin_amdgcn_fence(__ATOMIC_RELEASE, "agent");
;             asm volatile("s_waitcnt vmcnt(0)" ::: "memory");
;             const unsigned og = xb_add(&bar[XB_TOP], 1u);
;             const unsigned tg = og / nx;
;             if (og + 1u == (tg + 1u) * nx) xb_add(&bar[XB_TOPGEN], 1u);
;             else XB_SPIN(xb_ld(&bar[XB_TOPGEN]) == tg, bar);
;             __builtin_amdgcn_fence(__ATOMIC_ACQUIRE, "agent");
;             xb_add(&bar[XB_XGEN(b.x)], 1u);
;             asm volatile("s_waitcnt vmcnt(0)" ::: "memory");
;         } else {
;             XB_SPIN(xb_ld(&bar[XB_XGEN(b.x)]) == gen, bar);
.LBB0_826:
	s_or_b64 exec, exec, s[6:7]
	v_cvt_f32_u32_e32 v5, v3
	s_waitcnt vmcnt(0)
	v_readfirstlane_b32 s4, v4
	buffer_inv sc1
	v_sub_u32_e32 v4, 0, v3
	v_rcp_iflag_f32_e32 v5, v5
	v_add_u32_e32 v6, s4, v1
	v_mul_f32_e32 v5, 0x4f7ffffe, v5
	v_cvt_u32_f32_e32 v5, v5
	v_mul_lo_u32 v1, v4, v5
	v_mul_hi_u32 v1, v5, v1
	v_add_u32_e32 v1, v5, v1
	v_mul_hi_u32 v1, v6, v1
	v_mul_lo_u32 v4, v1, v3
	v_sub_u32_e32 v4, v6, v4
	v_add_u32_e32 v5, 1, v1
	v_cmp_ge_u32_e32 vcc, v4, v3
	s_nop 1
	v_cndmask_b32_e32 v1, v1, v5, vcc
	v_sub_u32_e32 v5, v4, v3
	v_cndmask_b32_e32 v4, v4, v5, vcc
	v_add_u32_e32 v5, 1, v1
	v_cmp_ge_u32_e32 vcc, v4, v3
	v_add_u32_e32 v4, 1, v6
	s_nop 0
	v_cndmask_b32_e32 v1, v1, v5, vcc
	v_mul_lo_u32 v5, v3, v1
	v_add_u32_e32 v3, v5, v3
	v_cmp_ne_u32_e32 vcc, v4, v3
	s_and_saveexec_b64 s[6:7], vcc
	s_xor_b64 s[6:7], exec, s[6:7]
	s_cbranch_execz .LBB0_840
	v_readlane_b32 s8, v253, 36
	v_readlane_b32 s9, v253, 37
	s_waitcnt lgkmcnt(0)
	s_nop 3
	global_load_dword v2, v99, s[8:9] sc1
	s_waitcnt vmcnt(0)
	v_cmp_eq_u32_e32 vcc, v2, v1
	s_and_saveexec_b64 s[8:9], vcc
	s_cbranch_execz .LBB0_839
	s_mov_b32 s4, 1
	s_mov_b64 s[10:11], 0
	s_branch .LBB0_830

; __device__ __forceinline__ unsigned xb_add(unsigned* p, unsigned v) { return __hip_atomic_fetch_add(p, v, __ATOMIC_RELAXED, __HIP_MEMORY_SCOPE_AGENT); }
; __device__ __forceinline__ void xcd_barrier(const XcdBarrier& b) {
;     ...
;             xb_add(&bar[XB_XGEN(b.x)], 1u);
;             asm volatile("s_waitcnt vmcnt(0)" ::: "memory");
.Lxcd_local_0:
	s_mov_b64 s[6:7], exec
	v_mbcnt_lo_u32_b32 v1, s6, 0
	v_mbcnt_hi_u32_b32 v1, s7, v1
	v_cmp_eq_u32_e32 vcc, 0, v1
	s_waitcnt vmcnt(0)
	s_and_saveexec_b64 s[8:9], vcc
	s_cbranch_execz .LBB0_859
	s_bcnt1_i32_b64 s4, s[6:7]
	v_readlane_b32 s6, v253, 36
	v_mov_b32_e32 v1, s4
	v_readlane_b32 s7, v253, 37
	s_nop 4
	global_atomic_add v99, v1, s[6:7]

; __device__ __forceinline__ unsigned xb_ld(unsigned* p)              { return __hip_atomic_load(p, __ATOMIC_RELAXED, __HIP_MEMORY_SCOPE_AGENT); }
; __device__ __forceinline__ unsigned xb_add(unsigned* p, unsigned v) { return __hip_atomic_fetch_add(p, v, __ATOMIC_RELAXED, __HIP_MEMORY_SCOPE_AGENT); }
; #define XB_SPIN(cond, bar) do { unsigned _sp = 0; while (cond) { __builtin_amdgcn_s_sleep(1); \
;     if ((++_sp & 255u) == 0u) { if (xb_ld(&(bar)[XB_TMO])) break; if (_sp > XB_SPIN_CAP) { atomicAdd(&(bar)[XB_TMO], 1u); break; } } } } while (0)
; __device__ __forceinline__ void xcd_barrier(const XcdBarrier& b) {
;     ...
;         const unsigned old = xb_add(&bar[XB_XSUB(b.x)], 1u);
;         const unsigned gen = old / nloc;
;         if (old + 1u == (gen + 1u) * nloc) {
;             __builtin_amdgcn_fence(__ATOMIC_RELEASE, "agent");
;             asm volatile("s_waitcnt vmcnt(0)" ::: "memory");
;             const unsigned og = xb_add(&bar[XB_TOP], 1u);
;             const unsigned tg = og / nx;
;             if (og + 1u == (tg + 1u) * nx) xb_add(&bar[XB_TOPGEN], 1u);
;             else XB_SPIN(xb_ld(&bar[XB_TOPGEN]) == tg, bar);
;             __builtin_amdgcn_fence(__ATOMIC_ACQUIRE, "agent");
;             xb_add(&bar[XB_XGEN(b.x)], 1u);
;             asm volatile("s_waitcnt vmcnt(0)" ::: "memory");
;         } else {
;             XB_SPIN(xb_ld(&bar[XB_XGEN(b.x)]) == gen, bar);
.LBB0_1077:
	s_or_b64 exec, exec, s[10:11]
	v_cvt_f32_u32_e32 v5, v3
	s_waitcnt vmcnt(0)
	v_readfirstlane_b32 s4, v4
	buffer_inv sc1
	v_sub_u32_e32 v4, 0, v3
	v_rcp_iflag_f32_e32 v5, v5
	v_add_u32_e32 v6, s4, v1
	v_mul_f32_e32 v5, 0x4f7ffffe, v5
	v_cvt_u32_f32_e32 v5, v5
	v_mul_lo_u32 v1, v4, v5
	v_mul_hi_u32 v1, v5, v1
	v_add_u32_e32 v1, v5, v1
	v_mul_hi_u32 v1, v6, v1
	v_mul_lo_u32 v4, v1, v3
	v_sub_u32_e32 v4, v6, v4
	v_add_u32_e32 v5, 1, v1
	v_cmp_ge_u32_e32 vcc, v4, v3
	s_nop 1
	v_cndmask_b32_e32 v1, v1, v5, vcc
	v_sub_u32_e32 v5, v4, v3
	v_cndmask_b32_e32 v4, v4, v5, vcc
	v_add_u32_e32 v5, 1, v1
	v_cmp_ge_u32_e32 vcc, v4, v3
	v_add_u32_e32 v4, 1, v6
	s_nop 0
	v_cndmask_b32_e32 v1, v1, v5, vcc
	v_mul_lo_u32 v5, v3, v1
	v_add_u32_e32 v3, v5, v3
	v_cmp_ne_u32_e32 vcc, v4, v3
	s_and_saveexec_b64 s[10:11], vcc
	s_xor_b64 s[10:11], exec, s[10:11]
	s_cbranch_execz .LBB0_1091
	v_readlane_b32 s14, v253, 36
	v_readlane_b32 s15, v253, 37
	s_waitcnt lgkmcnt(0)
	s_nop 3
	global_load_dword v2, v99, s[14:15] sc1
	s_waitcnt vmcnt(0)
	v_cmp_eq_u32_e32 vcc, v2, v1
	s_and_saveexec_b64 s[14:15], vcc
	s_cbranch_execz .LBB0_1090
	s_mov_b32 s4, 1
	s_mov_b64 s[34:35], 0
	s_branch .LBB0_1081

; __device__ __forceinline__ unsigned xb_ld(unsigned* p)              { return __hip_atomic_load(p, __ATOMIC_RELAXED, __HIP_MEMORY_SCOPE_AGENT); }
; #define XB_SPIN(cond, bar) do { unsigned _sp = 0; while (cond) { __builtin_amdgcn_s_sleep(1); \
;     if ((++_sp & 255u) == 0u) { if (xb_ld(&(bar)[XB_TMO])) break; if (_sp > XB_SPIN_CAP) { atomicAdd(&(bar)[XB_TMO], 1u); break; } } } } while (0)
; __device__ __forceinline__ void xcd_barrier(const XcdBarrier& b) {
;     ...
;         } else {
;             XB_SPIN(xb_ld(&bar[XB_XGEN(b.x)]) == gen, bar);
;             __builtin_amdgcn_fence(__ATOMIC_ACQUIRE, "agent");
;             asm volatile("s_waitcnt vmcnt(0)" ::: "memory");
.LBB0_1090:
	s_or_b64 exec, exec, s[14:15]
	s_waitcnt vmcnt(0)
	s_waitcnt vmcnt(0)

; __device__ __forceinline__ unsigned xb_add(unsigned* p, unsigned v) { return __hip_atomic_fetch_add(p, v, __ATOMIC_RELAXED, __HIP_MEMORY_SCOPE_AGENT); }
; __device__ __forceinline__ void xcd_barrier(const XcdBarrier& b) {
;     ...
;             xb_add(&bar[XB_XGEN(b.x)], 1u);
;             asm volatile("s_waitcnt vmcnt(0)" ::: "memory");
.Lxcd_local_2:
	s_mov_b64 s[10:11], exec
	v_mbcnt_lo_u32_b32 v1, s10, 0
	v_mbcnt_hi_u32_b32 v1, s11, v1
	v_cmp_eq_u32_e32 vcc, 0, v1
	s_waitcnt vmcnt(0)
	s_and_saveexec_b64 s[14:15], vcc
	s_cbranch_execz .LBB0_1110
	s_bcnt1_i32_b64 s4, s[10:11]
	v_readlane_b32 s10, v253, 36
	v_mov_b32_e32 v1, s4
	v_readlane_b32 s11, v253, 37
	s_nop 4
	global_atomic_add v99, v1, s[10:11]

; __device__ __forceinline__ unsigned xb_add(unsigned* p, unsigned v) { return __hip_atomic_fetch_add(p, v, __ATOMIC_RELAXED, __HIP_MEMORY_SCOPE_AGENT); }
; __device__ __forceinline__ void xcd_barrier(const XcdBarrier& b) {
;     ...
;             __builtin_amdgcn_fence(__ATOMIC_ACQUIRE, "agent");
;             xb_add(&bar[XB_XGEN(b.x)], 1u);
;             asm volatile("s_waitcnt vmcnt(0)" ::: "memory");
.LBB0_1925:
	s_or_b64 exec, exec, s[6:7]
	s_mov_b64 s[6:7], exec
	v_mbcnt_lo_u32_b32 v1, s6, 0
	v_mbcnt_hi_u32_b32 v1, s7, v1
	v_cmp_eq_u32_e32 vcc, 0, v1
	s_waitcnt vmcnt(0)
	s_and_saveexec_b64 s[8:9], vcc
	s_cbranch_execnz .LBB0_1926
	s_getpc_b64 s[98:99]
